# LayerNorm phase: the 16 row loads of a wave issued together with counted vmcnt waits instead of one load per wait
# speedup vs baseline: 1.0045x; 1.0014x over previous
.LBB0_670:
	v_add_co_u32_e32 v136, vcc, 0xffffc3f8, v100
	s_nop 1
	v_addc_co_u32_e32 v137, vcc, -1, v101, vcc
	v_add_co_u32_e32 v138, vcc, 0xffffd3f8, v100
	s_nop 1
	v_addc_co_u32_e32 v139, vcc, -1, v101, vcc
	v_add_co_u32_e32 v140, vcc, 0xffffe3f8, v100
	s_nop 1
	v_addc_co_u32_e32 v141, vcc, -1, v101, vcc
	v_add_co_u32_e32 v142, vcc, 0xfffff3f8, v100
	s_nop 1
	v_addc_co_u32_e32 v143, vcc, -1, v101, vcc
	global_load_dwordx4 v[34:37], v[136:137], off
	global_load_dwordx4 v[38:41], v[136:137], off offset:1024
	global_load_dwordx4 v[42:45], v[136:137], off offset:2048
	global_load_dwordx4 v[46:49], v[136:137], off offset:3072
	global_load_dwordx4 v[50:53], v[138:139], off
	global_load_dwordx4 v[54:57], v[138:139], off offset:1024
	global_load_dwordx4 v[58:61], v[138:139], off offset:2048
	global_load_dwordx4 v[62:65], v[138:139], off offset:3072
	global_load_dwordx4 v[66:69], v[140:141], off
	global_load_dwordx4 v[70:73], v[140:141], off offset:1024
	global_load_dwordx4 v[74:77], v[140:141], off offset:2048
	global_load_dwordx4 v[78:81], v[140:141], off offset:3072
	global_load_dwordx4 v[82:85], v[142:143], off
	global_load_dwordx4 v[86:89], v[142:143], off offset:1024
	global_load_dwordx4 v[90:93], v[142:143], off offset:2048
	global_load_dwordx4 v[94:97], v[142:143], off offset:3072
	s_mov_b32 s10, 0x3727c5ac
	s_mov_b32 s5, 0x800000
	s_waitcnt vmcnt(12)
	v_add_f32_e32 v0, v34, v35
	v_add_f32_e32 v0, v0, v36
	v_add_f32_e32 v0, v0, v37
	v_add_f32_e32 v144, v38, v39
	v_add_f32_e32 v144, v144, v40
	v_add_f32_e32 v0, 0, v0
	v_add_f32_e32 v144, v144, v41
	v_add_f32_e32 v0, v0, v144
	v_add_f32_e32 v144, v42, v43
	v_add_f32_e32 v144, v144, v44
	v_add_f32_e32 v144, v144, v45
	v_add_f32_e32 v0, v0, v144
	v_add_f32_e32 v144, v46, v47
	v_add_f32_e32 v144, v144, v48
	v_add_f32_e32 v144, v144, v49
	v_add_f32_e32 v0, v0, v144
	ds_swizzle_b32 v144, v0 offset:swizzle(SWAP,1)
	s_waitcnt lgkmcnt(0)
	v_add_f32_e32 v0, v0, v144
	ds_swizzle_b32 v144, v0 offset:swizzle(SWAP,2)
	s_waitcnt lgkmcnt(0)
	v_add_f32_e32 v0, v0, v144
	ds_swizzle_b32 v144, v0 offset:swizzle(SWAP,4)
	s_waitcnt lgkmcnt(0)
	v_add_f32_e32 v0, v0, v144
	ds_swizzle_b32 v144, v0 offset:swizzle(SWAP,8)
	s_waitcnt lgkmcnt(0)
	v_add_f32_e32 v0, v0, v144
	ds_swizzle_b32 v144, v0 offset:swizzle(SWAP,16)
	s_waitcnt lgkmcnt(0)
	v_add_f32_e32 v0, v0, v144
	s_waitcnt vmcnt(8)
	v_add_f32_e32 v144, v50, v51
	v_add_f32_e32 v144, v144, v52
	v_add_f32_e32 v144, v144, v53
	v_add_f32_e32 v145, 0, v144
	v_add_f32_e32 v144, v54, v55
	v_add_f32_e32 v144, v144, v56
	v_add_f32_e32 v144, v144, v57
	v_add_f32_e32 v145, v145, v144
	v_add_f32_e32 v144, v58, v59
	v_add_f32_e32 v144, v144, v60
	v_add_f32_e32 v144, v144, v61
	v_add_f32_e32 v145, v145, v144
	v_add_f32_e32 v144, v62, v63
	v_add_f32_e32 v144, v144, v64
	v_add_f32_e32 v144, v144, v65
	v_add_f32_e32 v102, v145, v144
	s_waitcnt vmcnt(4)
	v_add_f32_e32 v144, v66, v67
	v_add_f32_e32 v144, v144, v68
	v_add_f32_e32 v144, v144, v69
	v_add_f32_e32 v145, 0, v144
	v_add_f32_e32 v144, v70, v71
	v_add_f32_e32 v144, v144, v72
	v_add_f32_e32 v144, v144, v73
	v_add_f32_e32 v145, v145, v144
	v_add_f32_e32 v144, v74, v75
	v_add_f32_e32 v144, v144, v76
	v_add_f32_e32 v144, v144, v77
	v_add_f32_e32 v145, v145, v144
	v_add_f32_e32 v144, v78, v79
	v_add_f32_e32 v144, v144, v80
	v_add_f32_e32 v144, v144, v81
	v_add_f32_e32 v104, v145, v144
	s_waitcnt vmcnt(0)
	v_add_f32_e32 v144, v82, v83
	v_add_f32_e32 v144, v144, v84
	v_add_f32_e32 v144, v144, v85
	v_add_f32_e32 v145, 0, v144
	v_add_f32_e32 v144, v86, v87
	v_add_f32_e32 v144, v144, v88
	v_add_f32_e32 v144, v144, v89
	v_add_f32_e32 v145, v145, v144
	v_add_f32_e32 v144, v90, v91
	v_add_f32_e32 v144, v144, v92
	v_add_f32_e32 v144, v144, v93
	v_add_f32_e32 v105, v145, v144
	v_add_f32_e32 v106, v94, v95
	v_add_f32_e32 v106, v106, v96
	v_add_f32_e32 v106, v106, v97
	v_add_f32_e32 v105, v105, v106
	v_mov_b32_e32 v106, v0
	s_nop 1
	v_permlane32_swap_b32_e32 v0, v106
	v_add_f32_e32 v0, v0, v106
	ds_swizzle_b32 v106, v102 offset:swizzle(SWAP,1)
	v_mul_f32_e32 v0, 0x3a800000, v0
	v_pk_add_f32 v[130:131], v[34:35], v[0:1] op_sel_hi:[1,0] neg_lo:[0,1] neg_hi:[0,1]
	v_pk_add_f32 v[126:127], v[38:39], v[0:1] op_sel_hi:[1,0] neg_lo:[0,1] neg_hi:[0,1]
	v_pk_add_f32 v[132:133], v[36:37], v[0:1] op_sel_hi:[1,0] neg_lo:[0,1] neg_hi:[0,1]
	s_waitcnt lgkmcnt(0)
	v_add_f32_e32 v102, v102, v106
	ds_swizzle_b32 v106, v102 offset:swizzle(SWAP,2)
	v_mov_b32_e32 v36, v131
	v_mov_b32_e32 v37, v127
	v_pk_add_f32 v[128:129], v[40:41], v[0:1] op_sel_hi:[1,0] neg_lo:[0,1] neg_hi:[0,1]
	v_mov_b32_e32 v34, v130
	s_waitcnt lgkmcnt(0)
	v_add_f32_e32 v102, v102, v106
	ds_swizzle_b32 v106, v102 offset:swizzle(SWAP,4)
	v_mov_b32_e32 v35, v126
	v_pk_mul_f32 v[36:37], v[36:37], v[36:37]
	v_pk_add_f32 v[122:123], v[42:43], v[0:1] op_sel_hi:[1,0] neg_lo:[0,1] neg_hi:[0,1]
	v_pk_fma_f32 v[34:35], v[34:35], v[34:35], v[36:37]
	s_waitcnt lgkmcnt(0)
	v_add_f32_e32 v102, v102, v106
	ds_swizzle_b32 v106, v102 offset:swizzle(SWAP,8)
	v_mov_b32_e32 v36, v132
	v_mov_b32_e32 v37, v128
	v_pk_add_f32 v[114:115], v[46:47], v[0:1] op_sel_hi:[1,0] neg_lo:[0,1] neg_hi:[0,1]
	v_pk_fma_f32 v[34:35], v[36:37], v[36:37], v[34:35]
	s_waitcnt lgkmcnt(0)
	v_add_f32_e32 v102, v102, v106
	ds_swizzle_b32 v106, v102 offset:swizzle(SWAP,16)
	v_mov_b32_e32 v36, v133
	v_mov_b32_e32 v37, v129
	v_mov_b32_e32 v38, v115
	v_mov_b32_e32 v39, v123
	s_waitcnt lgkmcnt(0)
	v_add_f32_e32 v102, v102, v106
	v_mov_b32_e32 v106, v102
	v_pk_fma_f32 v[34:35], v[36:37], v[36:37], v[34:35]
	s_nop 0
	v_permlane32_swap_b32_e32 v102, v106
	v_add_f32_e32 v102, v102, v106
	ds_swizzle_b32 v106, v104 offset:swizzle(SWAP,1)
	v_pk_add_f32 v[124:125], v[44:45], v[0:1] op_sel_hi:[1,0] neg_lo:[0,1] neg_hi:[0,1]
	v_pk_add_f32 v[116:117], v[48:49], v[0:1] op_sel_hi:[1,0] neg_lo:[0,1] neg_hi:[0,1]
	v_mov_b32_e32 v36, v114
	v_mov_b32_e32 v37, v122
	s_waitcnt lgkmcnt(0)
	v_add_f32_e32 v104, v104, v106
	ds_swizzle_b32 v106, v104 offset:swizzle(SWAP,2)
	v_pk_mul_f32 v[38:39], v[38:39], v[38:39]
	v_mul_f32_e32 v102, 0x3a800000, v102
	v_pk_fma_f32 v[36:37], v[36:37], v[36:37], v[38:39]
	v_mov_b32_e32 v38, v116
	s_waitcnt lgkmcnt(0)
	v_add_f32_e32 v104, v104, v106
	ds_swizzle_b32 v106, v104 offset:swizzle(SWAP,4)
	v_mov_b32_e32 v39, v124
	v_pk_fma_f32 v[36:37], v[38:39], v[38:39], v[36:37]
	v_mov_b32_e32 v38, v117
	v_mov_b32_e32 v39, v125
	s_waitcnt lgkmcnt(0)
	v_add_f32_e32 v104, v104, v106
	ds_swizzle_b32 v106, v104 offset:swizzle(SWAP,8)
	v_pk_fma_f32 v[36:37], v[38:39], v[38:39], v[36:37]
	v_add_f32_e32 v34, v34, v35
	v_add_f32_e32 v34, v37, v34
	v_pk_add_f32 v[118:119], v[50:51], v[102:103] op_sel_hi:[1,0] neg_lo:[0,1] neg_hi:[0,1]
	s_waitcnt lgkmcnt(0)
	v_add_f32_e32 v104, v104, v106
	ds_swizzle_b32 v106, v104 offset:swizzle(SWAP,16)
	v_pk_add_f32 v[110:111], v[54:55], v[102:103] op_sel_hi:[1,0] neg_lo:[0,1] neg_hi:[0,1]
	v_pk_add_f32 v[120:121], v[52:53], v[102:103] op_sel_hi:[1,0] neg_lo:[0,1] neg_hi:[0,1]
	v_mov_b32_e32 v37, v111
	v_pk_add_f32 v[112:113], v[56:57], v[102:103] op_sel_hi:[1,0] neg_lo:[0,1] neg_hi:[0,1]
	s_waitcnt lgkmcnt(0)
	v_add_f32_e32 v104, v104, v106
	v_mov_b32_e32 v106, v104
	v_mov_b32_e32 v35, v110
	s_nop 0
	v_permlane32_swap_b32_e32 v104, v106
	v_add_f32_e32 v104, v104, v106
	ds_swizzle_b32 v106, v105 offset:swizzle(SWAP,1)
	v_pk_add_f32 v[62:63], v[62:63], v[102:103] op_sel_hi:[1,0] neg_lo:[0,1] neg_hi:[0,1]
	v_pk_add_f32 v[108:109], v[60:61], v[102:103] op_sel_hi:[1,0] neg_lo:[0,1] neg_hi:[0,1]
	v_mov_b32_e32 v38, v63
	v_pk_add_f32 v[64:65], v[64:65], v[102:103] op_sel_hi:[1,0] neg_lo:[0,1] neg_hi:[0,1]
	s_waitcnt lgkmcnt(0)
	v_add_f32_e32 v105, v105, v106
	ds_swizzle_b32 v106, v105 offset:swizzle(SWAP,2)
	v_mul_f32_e32 v104, 0x3a800000, v104
	s_waitcnt lgkmcnt(0)
	v_add_f32_e32 v105, v105, v106
	ds_swizzle_b32 v106, v105 offset:swizzle(SWAP,4)
	s_waitcnt lgkmcnt(0)
	v_add_f32_e32 v105, v105, v106
	ds_swizzle_b32 v106, v105 offset:swizzle(SWAP,8)
	s_waitcnt lgkmcnt(0)
	v_add_f32_e32 v105, v105, v106
	ds_swizzle_b32 v106, v105 offset:swizzle(SWAP,16)
	s_waitcnt lgkmcnt(0)
	v_add_f32_e32 v105, v105, v106
	v_mov_b32_e32 v106, v105
	s_nop 1
	v_permlane32_swap_b32_e32 v105, v106
	v_add_f32_e32 v105, v105, v106
	v_mul_f32_e32 v134, 0x3a800000, v105
	v_add_f32_e32 v105, v36, v34
	v_mov_b32_e32 v36, v119
	v_mov_b32_e32 v34, v118
	v_pk_mul_f32 v[36:37], v[36:37], v[36:37]
	v_pk_add_f32 v[106:107], v[58:59], v[102:103] op_sel_hi:[1,0] neg_lo:[0,1] neg_hi:[0,1]
	v_pk_fma_f32 v[34:35], v[34:35], v[34:35], v[36:37]
	v_mov_b32_e32 v36, v120
	v_mov_b32_e32 v37, v112
	v_pk_fma_f32 v[34:35], v[36:37], v[36:37], v[34:35]
	v_mov_b32_e32 v36, v121
	v_mov_b32_e32 v37, v113
	v_mov_b32_e32 v39, v107
	v_pk_fma_f32 v[34:35], v[36:37], v[36:37], v[34:35]
	v_mov_b32_e32 v36, v62
	v_mov_b32_e32 v37, v106
	v_pk_mul_f32 v[38:39], v[38:39], v[38:39]
	v_add_f32_e32 v34, v34, v35
	v_pk_fma_f32 v[36:37], v[36:37], v[36:37], v[38:39]
	v_mov_b32_e32 v38, v64
	v_mov_b32_e32 v39, v108
	v_pk_fma_f32 v[36:37], v[38:39], v[38:39], v[36:37]
	v_mov_b32_e32 v38, v65
	v_mov_b32_e32 v39, v109
	v_pk_fma_f32 v[36:37], v[38:39], v[38:39], v[36:37]
	v_pk_add_f32 v[66:67], v[66:67], v[104:105] op_sel_hi:[1,0] neg_lo:[0,1] neg_hi:[0,1]
	v_add_f32_e32 v34, v37, v34
	v_pk_add_f32 v[58:59], v[70:71], v[104:105] op_sel_hi:[1,0] neg_lo:[0,1] neg_hi:[0,1]
	v_add_f32_e32 v135, v36, v34
	v_mov_b32_e32 v36, v67
	v_mov_b32_e32 v37, v59
	v_pk_add_f32 v[68:69], v[68:69], v[104:105] op_sel_hi:[1,0] neg_lo:[0,1] neg_hi:[0,1]
	v_pk_add_f32 v[60:61], v[72:73], v[104:105] op_sel_hi:[1,0] neg_lo:[0,1] neg_hi:[0,1]
	v_mov_b32_e32 v34, v66
	v_mov_b32_e32 v35, v58
	v_pk_mul_f32 v[36:37], v[36:37], v[36:37]
	v_pk_add_f32 v[54:55], v[74:75], v[104:105] op_sel_hi:[1,0] neg_lo:[0,1] neg_hi:[0,1]
	v_pk_fma_f32 v[34:35], v[34:35], v[34:35], v[36:37]
	v_mov_b32_e32 v36, v68
	v_mov_b32_e32 v37, v60
	v_pk_add_f32 v[46:47], v[78:79], v[104:105] op_sel_hi:[1,0] neg_lo:[0,1] neg_hi:[0,1]
	v_pk_fma_f32 v[34:35], v[36:37], v[36:37], v[34:35]
	v_mov_b32_e32 v36, v69
	v_mov_b32_e32 v37, v61
	v_mov_b32_e32 v38, v47
	v_mov_b32_e32 v39, v55
	v_pk_fma_f32 v[34:35], v[36:37], v[36:37], v[34:35]
	v_pk_add_f32 v[56:57], v[76:77], v[104:105] op_sel_hi:[1,0] neg_lo:[0,1] neg_hi:[0,1]
	v_pk_add_f32 v[48:49], v[80:81], v[104:105] op_sel_hi:[1,0] neg_lo:[0,1] neg_hi:[0,1]
	v_mov_b32_e32 v36, v46
	v_mov_b32_e32 v37, v54
	v_pk_mul_f32 v[38:39], v[38:39], v[38:39]
	v_add_f32_e32 v34, v34, v35
	v_pk_fma_f32 v[36:37], v[36:37], v[36:37], v[38:39]
	v_mov_b32_e32 v38, v48
	v_mov_b32_e32 v39, v56
	v_pk_fma_f32 v[36:37], v[38:39], v[38:39], v[36:37]
	v_mov_b32_e32 v38, v49
	v_mov_b32_e32 v39, v57
	v_pk_fma_f32 v[36:37], v[38:39], v[38:39], v[36:37]
	v_pk_add_f32 v[50:51], v[82:83], v[134:135] op_sel_hi:[1,0] neg_lo:[0,1] neg_hi:[0,1]
	v_add_f32_e32 v34, v37, v34
	v_pk_add_f32 v[42:43], v[86:87], v[134:135] op_sel_hi:[1,0] neg_lo:[0,1] neg_hi:[0,1]
	v_add_f32_e32 v76, v36, v34
	v_mov_b32_e32 v36, v51
	v_mov_b32_e32 v37, v43
	v_pk_add_f32 v[52:53], v[84:85], v[134:135] op_sel_hi:[1,0] neg_lo:[0,1] neg_hi:[0,1]
	v_pk_add_f32 v[44:45], v[88:89], v[134:135] op_sel_hi:[1,0] neg_lo:[0,1] neg_hi:[0,1]
	v_mov_b32_e32 v34, v50
	v_mov_b32_e32 v35, v42
	v_pk_mul_f32 v[36:37], v[36:37], v[36:37]
	v_pk_add_f32 v[38:39], v[90:91], v[134:135] op_sel_hi:[1,0] neg_lo:[0,1] neg_hi:[0,1]
	v_pk_fma_f32 v[34:35], v[34:35], v[34:35], v[36:37]
	v_mov_b32_e32 v36, v52
	v_mov_b32_e32 v37, v44
	v_pk_fma_f32 v[34:35], v[36:37], v[36:37], v[34:35]
	v_mov_b32_e32 v36, v53
	v_mov_b32_e32 v37, v45
	v_pk_fma_f32 v[70:71], v[36:37], v[36:37], v[34:35]
	v_pk_add_f32 v[34:35], v[94:95], v[134:135] op_sel_hi:[1,0] neg_lo:[0,1] neg_hi:[0,1]
	v_mov_b32_e32 v75, v39
	v_mov_b32_e32 v74, v35
	v_pk_add_f32 v[40:41], v[92:93], v[134:135] op_sel_hi:[1,0] neg_lo:[0,1] neg_hi:[0,1]
	v_pk_add_f32 v[36:37], v[96:97], v[134:135] op_sel_hi:[1,0] neg_lo:[0,1] neg_hi:[0,1]
	v_mov_b32_e32 v72, v34
	v_mov_b32_e32 v73, v38
	v_pk_mul_f32 v[74:75], v[74:75], v[74:75]
	v_add_f32_e32 v70, v70, v71
	v_pk_fma_f32 v[72:73], v[72:73], v[72:73], v[74:75]
	v_mov_b32_e32 v74, v36
	v_mov_b32_e32 v75, v40
	v_pk_fma_f32 v[72:73], v[74:75], v[74:75], v[72:73]
	v_mov_b32_e32 v74, v37
	v_mov_b32_e32 v75, v41
	v_pk_fma_f32 v[72:73], v[74:75], v[74:75], v[72:73]
	v_mov_b64_e32 v[74:75], s[10:11]
	v_add_f32_e32 v70, v73, v70
	v_add_f32_e32 v78, v72, v70
	ds_swizzle_b32 v70, v105 offset:swizzle(SWAP,1)
	s_mov_b32 s10, 0x3a800000
	s_waitcnt lgkmcnt(0)
	v_add_f32_e32 v70, v105, v70
	ds_swizzle_b32 v71, v70 offset:swizzle(SWAP,2)
	s_waitcnt lgkmcnt(0)
	v_add_f32_e32 v70, v70, v71
	ds_swizzle_b32 v71, v70 offset:swizzle(SWAP,4)
	s_waitcnt lgkmcnt(0)
	v_add_f32_e32 v70, v70, v71
	ds_swizzle_b32 v71, v70 offset:swizzle(SWAP,8)
	s_waitcnt lgkmcnt(0)
	v_add_f32_e32 v70, v70, v71
	ds_swizzle_b32 v71, v70 offset:swizzle(SWAP,16)
	s_waitcnt lgkmcnt(0)
	v_add_f32_e32 v71, v70, v71
	ds_swizzle_b32 v70, v135 offset:swizzle(SWAP,1)
	v_mov_b32_e32 v73, v71
	s_waitcnt lgkmcnt(0)
	v_add_f32_e32 v70, v135, v70
	ds_swizzle_b32 v72, v70 offset:swizzle(SWAP,2)
	v_permlane32_swap_b32_e32 v71, v73
	s_waitcnt lgkmcnt(0)
	v_add_f32_e32 v70, v70, v72
	ds_swizzle_b32 v72, v70 offset:swizzle(SWAP,4)
	s_waitcnt lgkmcnt(0)
	v_add_f32_e32 v70, v70, v72
	ds_swizzle_b32 v72, v70 offset:swizzle(SWAP,8)
	s_waitcnt lgkmcnt(0)
	v_add_f32_e32 v70, v70, v72
	ds_swizzle_b32 v72, v70 offset:swizzle(SWAP,16)
	s_waitcnt lgkmcnt(0)
	v_add_f32_e32 v70, v70, v72
	v_mov_b32_e32 v72, v70
	s_nop 1
	v_permlane32_swap_b32_e32 v70, v72
	v_pk_add_f32 v[70:71], v[70:71], v[72:73]
	s_nop 0
	v_pk_fma_f32 v[70:71], v[70:71], s[10:11], v[74:75] op_sel_hi:[1,0,0]
	s_nop 0
	v_mul_f32_e32 v72, 0x4b800000, v71
	v_cmp_gt_f32_e64 s[48:49], s5, v71
	v_cmp_gt_f32_e32 vcc, s5, v70
	s_nop 0
	v_cndmask_b32_e64 v71, v71, v72, s[48:49]
	v_rsq_f32_e32 v71, v71
	s_nop 0
	v_mul_f32_e32 v72, 0x45800000, v71
	v_cndmask_b32_e64 v72, v71, v72, s[48:49]
	v_mul_f32_e32 v71, 0x4b800000, v70
	v_cndmask_b32_e32 v70, v70, v71, vcc
	v_rsq_f32_e32 v70, v70
	s_nop 0
	v_mul_f32_e32 v71, 0x45800000, v70
	v_cndmask_b32_e32 v70, v70, v71, vcc
	ds_swizzle_b32 v71, v76 offset:swizzle(SWAP,1)
	s_waitcnt lgkmcnt(0)
	v_add_f32_e32 v71, v76, v71
	ds_swizzle_b32 v73, v71 offset:swizzle(SWAP,2)
	s_waitcnt lgkmcnt(0)
	v_add_f32_e32 v71, v71, v73
	ds_swizzle_b32 v73, v71 offset:swizzle(SWAP,4)
	s_waitcnt lgkmcnt(0)
	v_add_f32_e32 v71, v71, v73
	ds_swizzle_b32 v73, v71 offset:swizzle(SWAP,8)
	s_waitcnt lgkmcnt(0)
	v_add_f32_e32 v71, v71, v73
	ds_swizzle_b32 v73, v71 offset:swizzle(SWAP,16)
	s_waitcnt lgkmcnt(0)
	v_add_f32_e32 v77, v71, v73
	ds_swizzle_b32 v71, v78 offset:swizzle(SWAP,1)
	v_mov_b32_e32 v79, v77
	s_waitcnt lgkmcnt(0)
	v_add_f32_e32 v71, v78, v71
	ds_swizzle_b32 v73, v71 offset:swizzle(SWAP,2)
	v_permlane32_swap_b32_e32 v77, v79
	s_waitcnt lgkmcnt(0)
	v_add_f32_e32 v71, v71, v73
	ds_swizzle_b32 v73, v71 offset:swizzle(SWAP,4)
	s_waitcnt lgkmcnt(0)
	v_add_f32_e32 v71, v71, v73
	ds_swizzle_b32 v73, v71 offset:swizzle(SWAP,8)
	s_waitcnt lgkmcnt(0)
	v_add_f32_e32 v71, v71, v73
	ds_swizzle_b32 v73, v71 offset:swizzle(SWAP,16)
	s_waitcnt lgkmcnt(0)
	v_add_f32_e32 v76, v71, v73
	v_mov_b32_e32 v78, v76
	s_nop 1
	v_permlane32_swap_b32_e32 v76, v78
	v_pk_add_f32 v[76:77], v[76:77], v[78:79]
	s_nop 0
	v_pk_fma_f32 v[74:75], v[76:77], s[10:11], v[74:75] op_sel_hi:[1,0,0]
	s_nop 0
	v_mul_f32_e32 v71, 0x4b800000, v75
	v_cmp_gt_f32_e64 s[48:49], s5, v75
	v_cmp_gt_f32_e32 vcc, s5, v74
	s_nop 0
	v_cndmask_b32_e64 v71, v75, v71, s[48:49]
	v_rsq_f32_e32 v71, v71
	s_nop 0
	v_mul_f32_e32 v73, 0x45800000, v71
	v_cndmask_b32_e64 v76, v71, v73, s[48:49]
	v_mul_f32_e32 v71, 0x4b800000, v74
	v_cndmask_b32_e32 v71, v74, v71, vcc
	v_rsq_f32_e32 v71, v71
	s_nop 0
	v_mul_f32_e32 v73, 0x45800000, v71
	v_cndmask_b32_e32 v74, v71, v73, vcc
	s_and_saveexec_b64 s[48:49], s[40:41]
	s_cbranch_execz .LBB0_669
	v_cndmask_b32_e64 v71, v134, v104, s[46:47]
	v_cndmask_b32_e64 v71, v71, v102, s[44:45]
	v_cndmask_b32_e64 v78, v71, v0, s[42:43]
	v_cndmask_b32_e64 v0, v74, v76, s[46:47]
	v_add_u32_e32 v80, s4, v103
	v_cndmask_b32_e64 v0, v0, v70, s[44:45]
	v_ashrrev_i32_e32 v81, 31, v80
	v_cndmask_b32_e64 v79, v0, v72, s[42:43]
	v_lshl_add_u64 v[80:81], v[80:81], 3, s[8:9]
	global_store_dwordx2 v[80:81], v[78:79], off
	s_branch .LBB0_669
